# v68 + attention second half-step: the last two QK^T MFMAs of the first chain issued one gap earlier so its results are readable right after the last MFMA (s_nop 5 -> s_nop 0)
# speedup vs baseline: 1.0056x; 1.0056x over previous
.LBB0_1607:
	s_add_i32 s22, s28, 0x2000
	s_cmpk_lg_i32 s28, 0x4000
	s_cselect_b32 s61, s22, 0
	v_add_f32_e32 v15, v116, v14
	v_add_u32_e32 v14, s29, v244
	ds_read_b64_tr_b16 v[196:197], v14 offset:24576
	ds_read_b64_tr_b16 v[198:199], v14 offset:25088
	v_add_f32_e32 v132, v87, v88
	v_cvt_pk_bf16_f32 v156, v96, v97
	v_cvt_pk_bf16_f32 v157, v98, v99
	v_mfma_f32_32x32x16_bf16 v[112:127], v[112:115], v[172:175], 0
	ds_read_b64_tr_b16 v[192:193], v14 offset:28672
	ds_read_b64_tr_b16 v[194:195], v14 offset:29184
	v_add_f32_e32 v96, v89, v132
	v_cvt_pk_bf16_f32 v158, v100, v101
	v_cvt_pk_bf16_f32 v159, v102, v103
	v_mfma_f32_32x32x16_bf16 v[128:143], v[128:131], v[172:175], 0
	ds_read_b64_tr_b16 v[188:189], v14 offset:25600
	ds_read_b64_tr_b16 v[190:191], v14 offset:26112
	v_add_f32_e32 v96, v90, v96
	v_cvt_pk_bf16_f32 v152, v104, v105
	v_cvt_pk_bf16_f32 v153, v106, v107
	v_mfma_f32_32x32x16_bf16 v[112:127], v[184:187], v[168:171], v[112:127]
	ds_read_b64_tr_b16 v[184:185], v14 offset:29696
	ds_read_b64_tr_b16 v[186:187], v14 offset:30208
	v_add_f32_e32 v96, v91, v96
	v_cvt_pk_bf16_f32 v154, v108, v109
	v_cvt_pk_bf16_f32 v155, v110, v111
	v_mfma_f32_32x32x16_bf16 v[128:143], v[176:179], v[168:171], v[128:143]
	ds_read_b64_tr_b16 v[176:177], v14 offset:26624
	ds_read_b64_tr_b16 v[178:179], v14 offset:27136
	v_add_f32_e32 v96, v92, v96
	v_cvt_pk_bf16_f32 v148, v80, v81
	v_cvt_pk_bf16_f32 v149, v82, v83
	v_mfma_f32_32x32x16_bf16 v[112:127], v[180:183], v[164:167], v[112:127]
	v_mfma_f32_32x32x16_bf16 v[128:143], v[6:9], v[164:167], v[128:143]
	ds_read_b64_tr_b16 v[212:213], v14 offset:30720
	ds_read_b64_tr_b16 v[214:215], v14 offset:31232
	v_add_f32_e32 v80, v93, v96
	v_cvt_pk_bf16_f32 v150, v84, v85
	v_cvt_pk_bf16_f32 v151, v86, v87
	v_mfma_f32_32x32x16_bf16 v[112:127], v[10:13], v[160:163], v[112:127]
	ds_read_b64_tr_b16 v[208:209], v14 offset:27648
	ds_read_b64_tr_b16 v[210:211], v14 offset:28160
	v_add_f32_e32 v80, v94, v80
	v_cvt_pk_bf16_f32 v144, v88, v89
	v_cvt_pk_bf16_f32 v145, v90, v91
	ds_read_b64_tr_b16 v[6:7], v14 offset:31744
	ds_read_b64_tr_b16 v[8:9], v14 offset:32256
	v_add_f32_e32 v10, v95, v80
	v_cvt_pk_bf16_f32 v146, v92, v93
	v_cvt_pk_bf16_f32 v147, v94, v95
	v_mfma_f32_32x32x16_bf16 v[128:143], v[2:5], v[160:163], v[128:143]
	s_nop 0
	v_add_f32_e64 v4, v112, -v228
	v_add_f32_e64 v5, v113, -v228
	v_pk_add_f32 v[98:99], v[114:115], v[228:229] op_sel_hi:[1,0] neg_lo:[0,1] neg_hi:[0,1]
	v_pk_add_f32 v[100:101], v[116:117], v[228:229] op_sel_hi:[1,0] neg_lo:[0,1] neg_hi:[0,1]
	v_pk_add_f32 v[102:103], v[118:119], v[228:229] op_sel_hi:[1,0] neg_lo:[0,1] neg_hi:[0,1]
	v_pk_add_f32 v[104:105], v[120:121], v[228:229] op_sel_hi:[1,0] neg_lo:[0,1] neg_hi:[0,1]
	v_pk_add_f32 v[106:107], v[122:123], v[228:229] op_sel_hi:[1,0] neg_lo:[0,1] neg_hi:[0,1]
	v_pk_add_f32 v[108:109], v[124:125], v[228:229] op_sel_hi:[1,0] neg_lo:[0,1] neg_hi:[0,1]
	v_pk_add_f32 v[110:111], v[126:127], v[228:229] op_sel_hi:[1,0] neg_lo:[0,1] neg_hi:[0,1]
	v_max_f32_e32 v11, v4, v5
	s_add_u32 s22, s30, 0xa0000
	v_pk_add_f32 v[2:3], v[128:129], v[228:229] op_sel_hi:[1,0] neg_lo:[0,1] neg_hi:[0,1]
	v_max3_f32 v12, v98, v99, v100
	v_pk_add_f32 v[82:83], v[130:131], v[228:229] op_sel_hi:[1,0] neg_lo:[0,1] neg_hi:[0,1]
	v_max3_f32 v11, v11, v101, v102
	v_pk_add_f32 v[84:85], v[132:133], v[228:229] op_sel_hi:[1,0] neg_lo:[0,1] neg_hi:[0,1]
	v_max3_f32 v12, v12, v103, v104
	v_pk_add_f32 v[86:87], v[134:135], v[228:229] op_sel_hi:[1,0] neg_lo:[0,1] neg_hi:[0,1]
	v_max3_f32 v11, v11, v105, v106
	v_pk_add_f32 v[88:89], v[136:137], v[228:229] op_sel_hi:[1,0] neg_lo:[0,1] neg_hi:[0,1]
	v_max3_f32 v12, v12, v107, v108
	v_pk_add_f32 v[90:91], v[138:139], v[228:229] op_sel_hi:[1,0] neg_lo:[0,1] neg_hi:[0,1]
	v_max3_f32 v11, v11, v109, v110
	v_pk_add_f32 v[92:93], v[140:141], v[228:229] op_sel_hi:[1,0] neg_lo:[0,1] neg_hi:[0,1]
	v_max3_f32 v12, v12, v111, v2
	v_pk_add_f32 v[94:95], v[142:143], v[228:229] op_sel_hi:[1,0] neg_lo:[0,1] neg_hi:[0,1]
	v_max3_f32 v11, v11, v3, v82
	v_max3_f32 v12, v12, v83, v84
	v_max3_f32 v11, v11, v85, v86
	v_max3_f32 v12, v12, v87, v88
	v_max3_f32 v11, v11, v89, v90
	v_max3_f32 v12, v12, v91, v92
	v_max3_f32 v11, v11, v94, v95
	v_max3_f32 v11, v11, v93, v12
	s_addc_u32 s23, s31, 0
	s_add_i32 s24, s28, s57
	v_mov_b32_e32 v12, v11
	s_mov_b32 s25, m0
	s_mov_b32 m0, s24
	s_nop 0
	global_load_lds_dwordx4 v241, s[22:23]
	s_mov_b32 m0, s25
	s_add_u32 s22, s62, 0x60000
	s_nop 0
	v_permlane32_swap_b32_e32 v11, v12
	s_addc_u32 s23, s63, 0
	s_add_i32 s24, s61, s58
	s_mov_b32 s25, m0
	s_mov_b32 m0, s24
	s_nop 0
	global_load_lds_dwordx4 v242, s[22:23]
	s_mov_b32 m0, s25
	s_add_u32 s22, s64, 0x60000
	v_max_f32_e32 v11, v11, v12
	s_addc_u32 s23, s65, 0
	s_add_i32 s24, s61, s59
	s_mov_b32 s25, m0
	s_mov_b32 m0, s24
	s_nop 0
	global_load_lds_dwordx4 v242, s[22:23]
	s_mov_b32 m0, s25
	v_cmp_lt_f32_e32 vcc, s35, v11
	s_cmp_lg_u64 vcc, 0
	v_add_f32_e32 v10, v15, v10
	s_cselect_b64 s[22:23], -1, 0
	s_cbranch_vccnz .LBB0_1615
